# attention main loop: running max folded into the QK accumulator init (no per-element subtract), O/l rescaled only when a tile raises the row max by more than 8 (exact online softmax, f32 state)
# speedup vs baseline: 1.0501x; 1.0178x over previous
.LBB0_2403:
	s_or_b64 exec, exec, s[24:25]
	v_sub_f32_e32 v136, 0, v118
	v_sub_f32_e32 v137, 0, v118
	v_sub_f32_e32 v138, 0, v118
	v_sub_f32_e32 v139, 0, v118
	v_sub_f32_e32 v140, 0, v118
	v_sub_f32_e32 v141, 0, v118
	v_sub_f32_e32 v142, 0, v118
	v_sub_f32_e32 v143, 0, v118
	v_sub_f32_e32 v144, 0, v118
	v_sub_f32_e32 v145, 0, v118
	v_sub_f32_e32 v146, 0, v118
	v_sub_f32_e32 v147, 0, v118
	v_sub_f32_e32 v148, 0, v118
	v_sub_f32_e32 v149, 0, v118
	v_sub_f32_e32 v150, 0, v118
	v_sub_f32_e32 v151, 0, v118
	s_waitcnt vmcnt(1)
	ds_write_b128 v46, v[32:35] offset:22528
	s_and_saveexec_b64 s[24:25], s[6:7]
	ds_write_b128 v45, v[64:67] offset:22528
	s_or_b64 exec, exec, s[24:25]
	s_xor_b64 s[24:25], s[26:27], -1
	s_mov_b64 s[26:27], 0x1800000
	s_sub_i32 s1, -3, s0
	v_and_b32_e32 v32, 7, v102
	v_lshl_add_u64 v[104:105], v[42:43], 0, s[26:27]
	s_add_u32 s26, s28, s10
	v_lshlrev_b32_e32 v32, 4, v32
	v_mov_b32_e32 v33, v193
	s_addc_u32 s27, s29, s11
	v_lshl_add_u64 v[32:33], v[40:41], 0, v[32:33]
	v_lshl_add_u64 v[32:33], s[26:27], 0, v[32:33]
	s_mov_b64 s[26:27], 0x1800080
	v_lshl_add_u64 v[106:107], v[32:33], 0, s[26:27]
	s_add_u32 s26, s28, s39
	s_addc_u32 s27, s29, s37
	v_lshl_add_u64 v[32:33], v[102:103], 4, s[26:27]
	v_ashrrev_i32_e32 v101, 31, v100
	v_mul_u32_u24_e32 v117, 0x90, v44
	v_lshl_add_u64 v[108:109], v[32:33], 0, s[70:71]
	s_mov_b32 s13, 1
	s_waitcnt vmcnt(0)
	ds_write_b128 v47, v[36:39] offset:35840
	s_waitcnt lgkmcnt(0)
	s_barrier
	global_load_dwordx4 v[92:95], v[108:109], off
	s_and_saveexec_b64 s[26:27], s[6:7]
	s_cbranch_execz .LBB0_2407

.LBB0_2407:
	s_or_b64 exec, exec, s[26:27]
	global_load_dwordx4 v[96:99], v[106:107], off
	s_add_i32 s26, s13, -1
	s_and_b32 s28, s13, 1
	v_cmp_le_i32_e32 vcc, s26, v114
	s_and_saveexec_b64 s[26:27], vcc
	s_cbranch_execz .LBB0_2409
	s_mul_i32 s29, s28, 0x5800
	s_add_i32 s29, s29, 0
	v_add3_u32 v119, s29, v116, v192
	ds_read_b128 v[32:35], v119 offset:6656
	ds_read_b128 v[36:39], v119
	ds_read_b128 v[120:123], v119 offset:32
	ds_read_b128 v[124:127], v119 offset:6688
	s_waitcnt lgkmcnt(2)
	v_mfma_f32_32x32x16_bf16 v[48:63], v[36:39], v[88:91], v[136:151]
	v_mfma_f32_32x32x16_bf16 v[32:47], v[32:35], v[88:91], v[136:151]
	s_waitcnt lgkmcnt(1)
	v_mfma_f32_32x32x16_bf16 v[48:63], v[120:123], v[84:87], v[48:63]
	s_waitcnt lgkmcnt(0)
	v_mfma_f32_32x32x16_bf16 v[32:47], v[124:127], v[84:87], v[32:47]
	ds_read_b128 v[120:123], v119 offset:64
	ds_read_b128 v[124:127], v119 offset:6720
	s_waitcnt lgkmcnt(1)
	v_mfma_f32_32x32x16_bf16 v[48:63], v[120:123], v[80:83], v[48:63]
	s_waitcnt lgkmcnt(0)
	v_mfma_f32_32x32x16_bf16 v[32:47], v[124:127], v[80:83], v[32:47]
	ds_read_b128 v[120:123], v119 offset:96
	ds_read_b128 v[124:127], v119 offset:6752
	s_waitcnt lgkmcnt(1)
	v_mfma_f32_32x32x16_bf16 v[48:63], v[120:123], v[76:79], v[48:63]
	s_waitcnt lgkmcnt(0)
	v_mfma_f32_32x32x16_bf16 v[32:47], v[124:127], v[76:79], v[32:47]
	ds_read_b128 v[120:123], v119 offset:128
	ds_read_b128 v[124:127], v119 offset:6784
	s_waitcnt lgkmcnt(1)
	v_mfma_f32_32x32x16_bf16 v[48:63], v[120:123], v[72:75], v[48:63]
	s_waitcnt lgkmcnt(0)
	v_mfma_f32_32x32x16_bf16 v[32:47], v[124:127], v[72:75], v[32:47]
	ds_read_b128 v[120:123], v119 offset:160
	ds_read_b128 v[124:127], v119 offset:6816
	s_waitcnt lgkmcnt(1)
	v_mfma_f32_32x32x16_bf16 v[48:63], v[120:123], v[68:71], v[48:63]
	s_waitcnt lgkmcnt(0)
	v_mfma_f32_32x32x16_bf16 v[32:47], v[124:127], v[68:71], v[32:47]
	v_add3_u32 v168, s29, v117, v192
	ds_read_b128 v[152:155], v168 offset:13312
	ds_read_b128 v[156:159], v168 offset:17920
	ds_read_b128 v[160:163], v168 offset:13344
	ds_read_b128 v[164:167], v168 offset:17952
	ds_read_b128 v[128:131], v168 offset:13376
	ds_read_b128 v[132:135], v168 offset:17984
	ds_read_b128 v[172:175], v168 offset:13408
	ds_read_b128 v[176:179], v168 offset:18016
	s_nop 1
	v_max_f32_e32 v119, v49, v49
	v_max_f32_e32 v120, v48, v48
	v_max_f32_e32 v119, v120, v119
	v_max3_f32 v119, v119, v50, v51
	v_max3_f32 v119, v119, v52, v53
	v_max3_f32 v119, v119, v54, v55
	v_max3_f32 v119, v119, v56, v57
	v_max3_f32 v119, v119, v58, v59
	v_max3_f32 v119, v119, v60, v61
	v_max3_f32 v119, v119, v62, v63
	v_max3_f32 v119, v119, v32, v33
	v_max3_f32 v119, v119, v34, v35
	v_max3_f32 v119, v119, v36, v37
	v_max3_f32 v119, v119, v38, v39
	v_max3_f32 v119, v119, v40, v41
	v_max3_f32 v119, v119, v42, v43
	v_max3_f32 v119, v119, v44, v45
	v_max3_f32 v119, v119, v46, v47
	v_mov_b32_e32 v120, v119
	s_nop 1
	v_permlane32_swap_b32_e32 v119, v120
	v_max_f32_e32 v119, v119, v120
	v_cmp_lt_f32_e32 vcc, 0x41000000, v119
	s_cbranch_vccnz .Lattn_rare
.Lattn_common:
	v_exp_f32_e32 v48, v48
	v_exp_f32_e32 v49, v49
	v_exp_f32_e32 v50, v50
	v_add_f32_e32 v169, 0, v48
	v_exp_f32_e32 v51, v51
	v_add_f32_e32 v169, v49, v169
	v_exp_f32_e32 v52, v52
	v_add_f32_e32 v169, v50, v169
	v_exp_f32_e32 v53, v53
	v_add_f32_e32 v169, v51, v169
	v_exp_f32_e32 v54, v54
	v_add_f32_e32 v169, v52, v169
	v_exp_f32_e32 v55, v55
	v_add_f32_e32 v169, v53, v169
	v_add_f32_e32 v169, v54, v169
	v_cvt_pk_bf16_f32 v180, v48, v49
	v_add_f32_e32 v169, v55, v169
	v_cvt_pk_bf16_f32 v181, v50, v51
	v_cvt_pk_bf16_f32 v182, v52, v53
	v_cvt_pk_bf16_f32 v183, v54, v55
	v_exp_f32_e32 v56, v56
	v_exp_f32_e32 v57, v57
	s_waitcnt lgkmcnt(6)
	v_mfma_f32_32x32x16_bf16 v[16:31], v[152:155], v[180:183], v[16:31]
	v_mfma_f32_32x32x16_bf16 v[0:15], v[156:159], v[180:183], v[0:15]
	v_exp_f32_e32 v58, v58
	v_add_f32_e32 v169, v56, v169
	v_exp_f32_e32 v59, v59
	v_add_f32_e32 v169, v57, v169
	v_exp_f32_e32 v60, v60
	v_add_f32_e32 v169, v58, v169
	v_exp_f32_e32 v61, v61
	v_add_f32_e32 v169, v59, v169
	v_exp_f32_e32 v62, v62
	v_add_f32_e32 v169, v60, v169
	v_exp_f32_e32 v63, v63
	v_add_f32_e32 v169, v61, v169
	v_add_f32_e32 v169, v62, v169
	v_cvt_pk_bf16_f32 v184, v56, v57
	v_add_f32_e32 v169, v63, v169
	v_cvt_pk_bf16_f32 v185, v58, v59
	v_cvt_pk_bf16_f32 v186, v60, v61
	v_cvt_pk_bf16_f32 v187, v62, v63
	v_exp_f32_e32 v32, v32
	v_exp_f32_e32 v33, v33
	s_waitcnt lgkmcnt(4)
	v_mfma_f32_32x32x16_bf16 v[16:31], v[160:163], v[184:187], v[16:31]
	v_mfma_f32_32x32x16_bf16 v[0:15], v[164:167], v[184:187], v[0:15]
	v_exp_f32_e32 v34, v34
	v_add_f32_e32 v169, v32, v169
	v_exp_f32_e32 v35, v35
	v_add_f32_e32 v169, v33, v169
	v_exp_f32_e32 v36, v36
	v_add_f32_e32 v169, v34, v169
	v_exp_f32_e32 v37, v37
	v_add_f32_e32 v169, v35, v169
	v_exp_f32_e32 v38, v38
	v_add_f32_e32 v169, v36, v169
	v_exp_f32_e32 v39, v39
	v_add_f32_e32 v169, v37, v169
	v_add_f32_e32 v169, v38, v169
	v_cvt_pk_bf16_f32 v180, v32, v33
	v_add_f32_e32 v169, v39, v169
	v_cvt_pk_bf16_f32 v181, v34, v35
	v_cvt_pk_bf16_f32 v182, v36, v37
	v_cvt_pk_bf16_f32 v183, v38, v39
	v_exp_f32_e32 v40, v40
	v_exp_f32_e32 v41, v41
	s_waitcnt lgkmcnt(2)
	v_mfma_f32_32x32x16_bf16 v[16:31], v[128:131], v[180:183], v[16:31]
	v_mfma_f32_32x32x16_bf16 v[0:15], v[132:135], v[180:183], v[0:15]
	v_exp_f32_e32 v42, v42
	v_add_f32_e32 v169, v40, v169
	v_exp_f32_e32 v43, v43
	v_add_f32_e32 v169, v41, v169
	v_exp_f32_e32 v44, v44
	v_add_f32_e32 v169, v42, v169
	v_exp_f32_e32 v45, v45
	v_add_f32_e32 v169, v43, v169
	v_exp_f32_e32 v46, v46
	v_add_f32_e32 v169, v44, v169
	v_exp_f32_e32 v47, v47
	v_add_f32_e32 v169, v45, v169
	v_add_f32_e32 v169, v46, v169
	v_cvt_pk_bf16_f32 v184, v40, v41
	v_add_f32_e32 v169, v47, v169
	v_cvt_pk_bf16_f32 v185, v42, v43
	v_cvt_pk_bf16_f32 v186, v44, v45
	v_cvt_pk_bf16_f32 v187, v46, v47
	v_add_f32_e32 v115, v115, v169
	s_nop 0
	s_waitcnt lgkmcnt(0)
	v_mfma_f32_32x32x16_bf16 v[16:31], v[172:175], v[184:187], v[16:31]
	v_mfma_f32_32x32x16_bf16 v[0:15], v[176:179], v[184:187], v[0:15]
	s_branch .Lattn_blk_end
.Lattn_rare:
	v_max_f32_e32 v170, 0, v119
	v_exp_f32_e64 v171, -v170
	v_add_f32_e32 v118, v118, v170
	v_sub_f32_e32 v48, v48, v170
	v_sub_f32_e32 v49, v49, v170
	v_sub_f32_e32 v50, v50, v170
	v_sub_f32_e32 v51, v51, v170
	v_sub_f32_e32 v52, v52, v170
	v_sub_f32_e32 v53, v53, v170
	v_sub_f32_e32 v54, v54, v170
	v_sub_f32_e32 v55, v55, v170
	v_sub_f32_e32 v56, v56, v170
	v_sub_f32_e32 v57, v57, v170
	v_sub_f32_e32 v58, v58, v170
	v_sub_f32_e32 v59, v59, v170
	v_sub_f32_e32 v60, v60, v170
	v_sub_f32_e32 v61, v61, v170
	v_sub_f32_e32 v62, v62, v170
	v_sub_f32_e32 v63, v63, v170
	v_sub_f32_e32 v32, v32, v170
	v_sub_f32_e32 v33, v33, v170
	v_sub_f32_e32 v34, v34, v170
	v_sub_f32_e32 v35, v35, v170
	v_sub_f32_e32 v36, v36, v170
	v_sub_f32_e32 v37, v37, v170
	v_sub_f32_e32 v38, v38, v170
	v_sub_f32_e32 v39, v39, v170
	v_sub_f32_e32 v40, v40, v170
	v_sub_f32_e32 v41, v41, v170
	v_sub_f32_e32 v42, v42, v170
	v_sub_f32_e32 v43, v43, v170
	v_sub_f32_e32 v44, v44, v170
	v_sub_f32_e32 v45, v45, v170
	v_sub_f32_e32 v46, v46, v170
	v_sub_f32_e32 v47, v47, v170
	v_sub_f32_e32 v136, 0, v118
	v_sub_f32_e32 v137, 0, v118
	v_sub_f32_e32 v138, 0, v118
	v_sub_f32_e32 v139, 0, v118
	v_sub_f32_e32 v140, 0, v118
	v_sub_f32_e32 v141, 0, v118
	v_sub_f32_e32 v142, 0, v118
	v_sub_f32_e32 v143, 0, v118
	v_sub_f32_e32 v144, 0, v118
	v_sub_f32_e32 v145, 0, v118
	v_sub_f32_e32 v146, 0, v118
	v_sub_f32_e32 v147, 0, v118
	v_sub_f32_e32 v148, 0, v118
	v_sub_f32_e32 v149, 0, v118
	v_sub_f32_e32 v150, 0, v118
	v_sub_f32_e32 v151, 0, v118
	v_mul_f32_e32 v0, v171, v0
	v_mul_f32_e32 v1, v171, v1
	v_mul_f32_e32 v2, v171, v2
	v_mul_f32_e32 v3, v171, v3
	v_mul_f32_e32 v4, v171, v4
	v_mul_f32_e32 v5, v171, v5
	v_mul_f32_e32 v6, v171, v6
	v_mul_f32_e32 v7, v171, v7
	v_mul_f32_e32 v8, v171, v8
	v_mul_f32_e32 v9, v171, v9
	v_mul_f32_e32 v10, v171, v10
	v_mul_f32_e32 v11, v171, v11
	v_mul_f32_e32 v12, v171, v12
	v_mul_f32_e32 v13, v171, v13
	v_mul_f32_e32 v14, v171, v14
	v_mul_f32_e32 v15, v171, v15
	v_mul_f32_e32 v16, v171, v16
	v_mul_f32_e32 v17, v171, v17
	v_mul_f32_e32 v18, v171, v18
	v_mul_f32_e32 v19, v171, v19
	v_mul_f32_e32 v20, v171, v20
	v_mul_f32_e32 v21, v171, v21
	v_mul_f32_e32 v22, v171, v22
	v_mul_f32_e32 v23, v171, v23
	v_mul_f32_e32 v24, v171, v24
	v_mul_f32_e32 v25, v171, v25
	v_mul_f32_e32 v26, v171, v26
	v_mul_f32_e32 v27, v171, v27
	v_mul_f32_e32 v28, v171, v28
	v_mul_f32_e32 v29, v171, v29
	v_mul_f32_e32 v30, v171, v30
	v_mul_f32_e32 v31, v171, v31
	v_mul_f32_e32 v115, v171, v115
	s_branch .Lattn_common
.Lattn_blk_end:
.LBB0_2409:
	s_or_b64 exec, exec, s[26:27]
	s_xor_b32 s26, s28, 1
	s_mulk_i32 s26, 0x5800
	s_add_i32 s28, s26, 0
	v_add_u32_e32 v32, s28, v112
	s_waitcnt vmcnt(1)
	ds_write_b128 v32, v[92:95]
	s_and_saveexec_b64 s[26:27], s[6:7]
	v_add_u32_e32 v32, s28, v111
	ds_write_b128 v32, v[64:67]
	s_or_b64 exec, exec, s[26:27]
	v_add_u32_e32 v32, s28, v113
	s_add_i32 s28, s13, 1
	s_add_i32 s26, s1, s28
	v_lshl_add_u64 v[106:107], v[106:107], 0, s[80:81]
	s_cmp_eq_u32 s26, 1
	v_lshl_add_u64 v[108:109], v[108:109], 0, s[70:71]
	s_waitcnt vmcnt(0)
	ds_write_b128 v32, v[96:99] offset:13312
	s_waitcnt lgkmcnt(0)
	s_barrier
	s_cbranch_scc1 .LBB0_2413
	s_mov_b32 s13, s28
	global_load_dwordx4 v[92:95], v[108:109], off
	s_and_saveexec_b64 s[26:27], s[6:7]
	s_cbranch_execnz .LBB0_2406
	s_branch .LBB0_2407
